# fold_pool task order permuted so the 8 waves of a workgroup share one even_w_out column slice (L1/L2 reuse) (on top of v9)
# speedup vs baseline: 1.0030x; 1.0030x over previous
; __device__ __forceinline__ void fold_pool(int worker, int nworkers, int lane) {
;     ...
;     for (int w = worker; w < 1024; w += nworkers) {
;         const int k4 = __builtin_amdgcn_readfirstlane(w >> 3), ec = __builtin_amdgcn_readfirstlane(w & 7), kidx0 = k4 * 4, g = kidx0 >> 7;
;         const float* pr = pw + (size_t)kidx0 * 128; const float* sc = psc + g * 128; const float* wc = wo + (size_t)(g * 128) * D + ec * 256 + lane * 4;
;         f32x4 s[4];
; #pragma unroll
;         for (int i = 0; i < 4; ++i) s[i] = (f32x4){0.f, 0.f, 0.f, 0.f};
; #pragma unroll 8
;         for (int j = 0; j < 128; ++j) {
;             const f32x4 b = *(const f32x4*)(wc + (size_t)j * D) * sc[j];
; #pragma unroll
;             for (int i = 0; i < 4; ++i) s[i] = s[i] + b * pr[i * 128 + j];
.LBB0_740:
	s_and_b32 s6, s18, 7
	s_lshr_b32 s7, s18, 3
	s_and_b32 s9, s7, 7
	s_lshr_b32 s7, s7, 3
	s_lshl_b32 s7, s7, 3
	s_add_u32 s7, s7, s6
	s_lshl_b32 s7, s7, 3
	s_or_b32 s18, s7, s9
	v_readlane_b32 s6, v253, 1
	v_readlane_b32 s7, v253, 2
	s_nop 4
	s_load_dwordx2 s[24:25], s[6:7], 0x68
	s_ashr_i32 s9, s18, 1
	s_and_b32 s4, s9, -4
	s_and_b32 s22, s9, 0xffffff80
	s_ashr_i32 s5, s4, 31
	s_ashr_i32 s23, s22, 31
	s_lshl_b64 s[6:7], s[4:5], 9
	s_add_u32 s10, s56, s6
	s_addc_u32 s11, s57, s7
	s_lshl_b64 s[6:7], s[22:23], 13
	s_lshl_b64 s[22:23], s[22:23], 2
	s_add_u32 s22, s58, s22
	s_addc_u32 s23, s59, s23
	s_and_b32 s9, s18, 7
	s_lshl_b32 s9, s9, 10
	s_or_b32 s6, s6, s9
	s_waitcnt lgkmcnt(0)
	s_add_u32 s24, s24, s6
	s_addc_u32 s25, s25, s7
	v_lshlrev_b32_e32 v2, 4, v175
	v_mov_b32_e32 v28, 0
	v_mov_b32_e32 v29, 0
	v_mov_b32_e32 v26, 0
	v_mov_b32_e32 v27, 0
	v_mov_b32_e32 v30, 0
	v_mov_b32_e32 v31, 0
	v_mov_b32_e32 v10, 0
	v_mov_b32_e32 v11, 0
	v_mov_b32_e32 v32, 0
	v_mov_b32_e32 v33, 0
	v_mov_b32_e32 v14, 0
	v_mov_b32_e32 v15, 0
	v_mov_b32_e32 v34, 0
	v_mov_b32_e32 v35, 0
	v_mov_b32_e32 v18, 0
	v_mov_b32_e32 v19, 0
	s_mov_b32 s9, 0
	global_load_dwordx4 v[68:71], v2, s[24:25]
	s_add_u32 s24, s24, 0x2000
	s_addc_u32 s25, s25, 0
	global_load_dwordx4 v[72:75], v2, s[24:25]
	s_add_u32 s24, s24, 0x2000
	s_addc_u32 s25, s25, 0
	global_load_dwordx4 v[76:79], v2, s[24:25]
	s_add_u32 s24, s24, 0x2000
	s_addc_u32 s25, s25, 0
	global_load_dwordx4 v[80:83], v2, s[24:25]
	s_add_u32 s24, s24, 0x2000
	s_addc_u32 s25, s25, 0
	global_load_dwordx4 v[84:87], v2, s[24:25]
	s_add_u32 s24, s24, 0x2000
	s_addc_u32 s25, s25, 0
	global_load_dwordx4 v[88:91], v2, s[24:25]
	s_add_u32 s24, s24, 0x2000
	s_addc_u32 s25, s25, 0
	global_load_dwordx4 v[92:95], v2, s[24:25]
	s_add_u32 s24, s24, 0x2000
	s_addc_u32 s25, s25, 0
	global_load_dwordx4 v[96:99], v2, s[24:25]
	s_add_u32 s24, s24, 0x2000
	s_addc_u32 s25, s25, 0
	global_load_dwordx4 v[100:103], v1, s[22:23]
	global_load_dwordx4 v[104:107], v1, s[22:23] offset:16
	s_add_u32 s22, s22, 32
	s_addc_u32 s23, s23, 0
	global_load_dwordx4 v[108:111], v1, s[10:11] offset:0
	global_load_dwordx4 v[112:115], v1, s[10:11] offset:16
	global_load_dwordx4 v[116:119], v1, s[10:11] offset:512
	global_load_dwordx4 v[120:123], v1, s[10:11] offset:528
	global_load_dwordx4 v[124:127], v1, s[10:11] offset:1024
	global_load_dwordx4 v[128:131], v1, s[10:11] offset:1040
	global_load_dwordx4 v[132:135], v1, s[10:11] offset:1536
	global_load_dwordx4 v[136:139], v1, s[10:11] offset:1552
	s_add_u32 s10, s10, 32
	s_addc_u32 s11, s11, 0
